# P2 WY solve: previous-block update loop double-buffered (coefficients and x prefetched one step ahead)
# speedup vs baseline: 1.0075x; 1.0030x over previous
.LBB0_441:
	s_max_u32 s7, s8, 1
	s_and_b32 vcc_lo, s7, -16
	s_mov_b32 vcc_hi, 0
	s_mov_b32 s15, s9
	v_mov_b32_e32 v18, v132
	s_mov_b32 s10, s14
	v_mov_b32_e32 v19, s10
	ds_read_b32 v36, v18
	ds_read_b128 v[20:23], v19
	ds_read_b128 v[24:27], v19 offset:16
	ds_read_b128 v[28:31], v19 offset:32
	ds_read_b128 v[32:35], v19 offset:48
.LBB0_442:
	ds_read_b32 v37, v18 offset:528
	ds_read_b128 v[240:243], v19 offset:272
	ds_read_b128 v[244:247], v19 offset:288
	ds_read_b128 v[248:251], v19 offset:304
	ds_read_b128 v[252:255], v19 offset:320
	s_mov_b32 s6, s15
	s_add_i32 vcc_hi, vcc_hi, 4
	s_addk_i32 s10, 0x440
	s_addk_i32 s15, 0x440
	s_waitcnt lgkmcnt(5)
	v_pk_fma_f32 v[0:1], v[36:37], v[20:21], v[0:1] op_sel_hi:[0,1,1] neg_lo:[1,0,0] neg_hi:[1,0,0]
	v_pk_fma_f32 v[4:5], v[36:37], v[24:25], v[4:5] op_sel_hi:[0,1,1] neg_lo:[1,0,0] neg_hi:[1,0,0]
	v_pk_fma_f32 v[8:9], v[36:37], v[28:29], v[8:9] op_sel_hi:[0,1,1] neg_lo:[1,0,0] neg_hi:[1,0,0]
	v_pk_fma_f32 v[12:13], v[36:37], v[32:33], v[12:13] op_sel_hi:[0,1,1] neg_lo:[1,0,0] neg_hi:[1,0,0]
	v_pk_fma_f32 v[2:3], v[36:37], v[22:23], v[2:3] op_sel_hi:[0,1,1] neg_lo:[1,0,0] neg_hi:[1,0,0]
	v_pk_fma_f32 v[6:7], v[36:37], v[26:27], v[6:7] op_sel_hi:[0,1,1] neg_lo:[1,0,0] neg_hi:[1,0,0]
	v_pk_fma_f32 v[10:11], v[36:37], v[30:31], v[10:11] op_sel_hi:[0,1,1] neg_lo:[1,0,0] neg_hi:[1,0,0]
	v_pk_fma_f32 v[14:15], v[36:37], v[34:35], v[14:15] op_sel_hi:[0,1,1] neg_lo:[1,0,0] neg_hi:[1,0,0]
	ds_read_b32 v36, v18 offset:1056
	ds_read_b128 v[20:23], v19 offset:544
	ds_read_b128 v[24:27], v19 offset:560
	ds_read_b128 v[28:31], v19 offset:576
	ds_read_b128 v[32:35], v19 offset:592
	s_waitcnt lgkmcnt(5)
	v_pk_fma_f32 v[0:1], v[36:37], v[240:241], v[0:1] op_sel:[1,0,0] op_sel_hi:[1,1,1] neg_lo:[1,0,0] neg_hi:[1,0,0]
	v_pk_fma_f32 v[4:5], v[36:37], v[244:245], v[4:5] op_sel:[1,0,0] op_sel_hi:[1,1,1] neg_lo:[1,0,0] neg_hi:[1,0,0]
	v_pk_fma_f32 v[8:9], v[36:37], v[248:249], v[8:9] op_sel:[1,0,0] op_sel_hi:[1,1,1] neg_lo:[1,0,0] neg_hi:[1,0,0]
	v_pk_fma_f32 v[12:13], v[36:37], v[252:253], v[12:13] op_sel:[1,0,0] op_sel_hi:[1,1,1] neg_lo:[1,0,0] neg_hi:[1,0,0]
	v_pk_fma_f32 v[2:3], v[36:37], v[242:243], v[2:3] op_sel:[1,0,0] op_sel_hi:[1,1,1] neg_lo:[1,0,0] neg_hi:[1,0,0]
	v_pk_fma_f32 v[6:7], v[36:37], v[246:247], v[6:7] op_sel:[1,0,0] op_sel_hi:[1,1,1] neg_lo:[1,0,0] neg_hi:[1,0,0]
	v_pk_fma_f32 v[10:11], v[36:37], v[250:251], v[10:11] op_sel:[1,0,0] op_sel_hi:[1,1,1] neg_lo:[1,0,0] neg_hi:[1,0,0]
	v_pk_fma_f32 v[14:15], v[36:37], v[254:255], v[14:15] op_sel:[1,0,0] op_sel_hi:[1,1,1] neg_lo:[1,0,0] neg_hi:[1,0,0]
	ds_read_b32 v37, v18 offset:1584
	ds_read_b128 v[240:243], v19 offset:816
	ds_read_b128 v[244:247], v19 offset:832
	ds_read_b128 v[248:251], v19 offset:848
	ds_read_b128 v[252:255], v19 offset:864
	s_waitcnt lgkmcnt(5)
	v_pk_fma_f32 v[0:1], v[36:37], v[20:21], v[0:1] op_sel_hi:[0,1,1] neg_lo:[1,0,0] neg_hi:[1,0,0]
	v_pk_fma_f32 v[4:5], v[36:37], v[24:25], v[4:5] op_sel_hi:[0,1,1] neg_lo:[1,0,0] neg_hi:[1,0,0]
	v_pk_fma_f32 v[8:9], v[36:37], v[28:29], v[8:9] op_sel_hi:[0,1,1] neg_lo:[1,0,0] neg_hi:[1,0,0]
	v_pk_fma_f32 v[12:13], v[36:37], v[32:33], v[12:13] op_sel_hi:[0,1,1] neg_lo:[1,0,0] neg_hi:[1,0,0]
	v_pk_fma_f32 v[2:3], v[36:37], v[22:23], v[2:3] op_sel_hi:[0,1,1] neg_lo:[1,0,0] neg_hi:[1,0,0]
	v_pk_fma_f32 v[6:7], v[36:37], v[26:27], v[6:7] op_sel_hi:[0,1,1] neg_lo:[1,0,0] neg_hi:[1,0,0]
	v_pk_fma_f32 v[10:11], v[36:37], v[30:31], v[10:11] op_sel_hi:[0,1,1] neg_lo:[1,0,0] neg_hi:[1,0,0]
	v_pk_fma_f32 v[14:15], v[36:37], v[34:35], v[14:15] op_sel_hi:[0,1,1] neg_lo:[1,0,0] neg_hi:[1,0,0]
	ds_read_b32 v36, v18 offset:2112
	ds_read_b128 v[20:23], v19 offset:1088
	ds_read_b128 v[24:27], v19 offset:1104
	ds_read_b128 v[28:31], v19 offset:1120
	ds_read_b128 v[32:35], v19 offset:1136
	v_mov_b32_e32 v19, s10
	v_add_u32_e32 v18, 0x840, v18
	s_waitcnt lgkmcnt(5)
	v_pk_fma_f32 v[0:1], v[36:37], v[240:241], v[0:1] op_sel:[1,0,0] op_sel_hi:[1,1,1] neg_lo:[1,0,0] neg_hi:[1,0,0]
	v_pk_fma_f32 v[4:5], v[36:37], v[244:245], v[4:5] op_sel:[1,0,0] op_sel_hi:[1,1,1] neg_lo:[1,0,0] neg_hi:[1,0,0]
	v_pk_fma_f32 v[8:9], v[36:37], v[248:249], v[8:9] op_sel:[1,0,0] op_sel_hi:[1,1,1] neg_lo:[1,0,0] neg_hi:[1,0,0]
	v_pk_fma_f32 v[12:13], v[36:37], v[252:253], v[12:13] op_sel:[1,0,0] op_sel_hi:[1,1,1] neg_lo:[1,0,0] neg_hi:[1,0,0]
	v_pk_fma_f32 v[2:3], v[36:37], v[242:243], v[2:3] op_sel:[1,0,0] op_sel_hi:[1,1,1] neg_lo:[1,0,0] neg_hi:[1,0,0]
	v_pk_fma_f32 v[6:7], v[36:37], v[246:247], v[6:7] op_sel:[1,0,0] op_sel_hi:[1,1,1] neg_lo:[1,0,0] neg_hi:[1,0,0]
	v_pk_fma_f32 v[10:11], v[36:37], v[250:251], v[10:11] op_sel:[1,0,0] op_sel_hi:[1,1,1] neg_lo:[1,0,0] neg_hi:[1,0,0]
	v_pk_fma_f32 v[14:15], v[36:37], v[254:255], v[14:15] op_sel:[1,0,0] op_sel_hi:[1,1,1] neg_lo:[1,0,0] neg_hi:[1,0,0]
	s_cmp_lg_u32 vcc_lo, vcc_hi
	s_cbranch_scc1 .LBB0_442
	s_waitcnt lgkmcnt(0)
	s_max_u32 s10, s33, 1
	s_bitcmp0_b32 s10, 0
	s_cbranch_scc1 .LBB0_375
	s_and_b32 s7, s7, 1
	s_mulk_i32 s7, 0x210
	s_mov_b32 s10, 0
